# lane^32 exchanges in the attention loops via v_permlane32_swap instead of ds_bpermute
# speedup vs baseline: 1.0184x; 1.0032x over previous
; template <int MODE  > ...
;     ...
;             for (int kk = 0; kk < 4; ++kk) {
;                 const bf16x8 k0 = *(const LAS bf16x8*)(kb + col * KPITCH + kk * 16 + h * 8);
;                 const bf16x8 k1 = *(const LAS bf16x8*)(kb + (32 + col) * KPITCH + kk * 16 + h * 8);
;                 s0 = __builtin_amdgcn_mfma_f32_32x32x16_bf16(k0, qf[kk], s0, 0, 0, 0);
;                 s1 = __builtin_amdgcn_mfma_f32_32x32x16_bf16(k1, qf[kk], s1, 0, 0, 0);
;             }
;             if (MODE != 3) {
;                 float mx = fmaxf(s0[0], s1[0]);
; #pragma unroll
;                 for (int i = 1; i < 16; ++i) mx = fmaxf(mx, fmaxf(s0[i], s1[i]));
;                 mx = fmaxf(mx, shflx(mx, 32, lane));
;                 float alpha = 1.f;
;                 if (__builtin_amdgcn_ballot_w64(fresh || mx > 0.f) != 0ull) {
;                     const float moldr = fresh ? -1e29f : 0.f, mnewr = fmaxf(moldr, mx);
;                     alpha = __builtin_amdgcn_exp2f(moldr - mnewr);
;                     st.m = mest + mnewr;
; #pragma unroll
;                     for (int i = 0; i < 16; ++i) { s0[i] = __builtin_amdgcn_exp2f(s0[i] - mnewr); s1[i] = __builtin_amdgcn_exp2f(s1[i] - mnewr); }
;                     st.o0 *= alpha; st.o1 *= alpha;
;                 } else {
; #pragma unroll
;                     for (int i = 0; i < 16; ++i) { s0[i] = __builtin_amdgcn_exp2f(s0[i]); s1[i] = __builtin_amdgcn_exp2f(s1[i]); }
;                 }
;                 { typedef float f32x8 __attribute__((ext_vector_type(8)));
;                   const f32x16 t16 = s0 + s1;
;                   const f32x8 t8 = __builtin_shufflevector(t16, t16, 0, 1, 2, 3, 4, 5, 6, 7) + __builtin_shufflevector(t16, t16, 8, 9, 10, 11, 12, 13, 14, 15);
;                   const f32x4 t4 = __builtin_shufflevector(t8, t8, 0, 1, 2, 3) + __builtin_shufflevector(t8, t8, 4, 5, 6, 7);
;                   float ps = (t4[0] + t4[1]) + (t4[2] + t4[3]);
;                   ps += shflx(ps, 32, lane);
;                   st.l = st.l * alpha + ps; }
;                 bf16x8 pf[4];
; #pragma unroll
;                 for (int kk = 0; kk < 4; ++kk) {
;                     u32x4 pw;
;                     if (kk < 2) { pw.x = pk2(s0[8 * kk], s0[8 * kk + 1]); pw.y = pk2(s0[8 * kk + 2], s0[8 * kk + 3]); pw.z = pk2(s0[8 * kk + 4], s0[8 * kk + 5]); pw.w = pk2(s0[8 * kk + 6], s0[8 * kk + 7]); }
.Lm1_qk:
	s_waitcnt lgkmcnt(7)
	v_mfma_f32_32x32x16_bf16 v[50:65], v[66:69], v[144:147], v[50:65]
	s_waitcnt lgkmcnt(6)
	v_mfma_f32_32x32x16_bf16 v[2:17], v[70:73], v[144:147], v[2:17]
	s_waitcnt lgkmcnt(5)
	v_mfma_f32_32x32x16_bf16 v[50:65], v[74:77], v[148:151], v[50:65]
	s_waitcnt lgkmcnt(4)
	v_mfma_f32_32x32x16_bf16 v[2:17], v[78:81], v[148:151], v[2:17]
	s_waitcnt lgkmcnt(3)
	v_mfma_f32_32x32x16_bf16 v[50:65], v[82:85], v[152:155], v[50:65]
	s_waitcnt lgkmcnt(2)
	v_mfma_f32_32x32x16_bf16 v[2:17], v[86:89], v[152:155], v[2:17]
	s_waitcnt lgkmcnt(1)
	v_mfma_f32_32x32x16_bf16 v[50:65], v[90:93], v[156:159], v[50:65]
	s_waitcnt lgkmcnt(0)
	v_mfma_f32_32x32x16_bf16 v[2:17], v[94:97], v[156:159], v[2:17]
	ds_read_b64_tr_b16 v[66:67], v225 offset:18432
	ds_read_b64_tr_b16 v[68:69], v225 offset:19968
	ds_read_b64_tr_b16 v[70:71], v225 offset:18496
	ds_read_b64_tr_b16 v[72:73], v225 offset:20032
	ds_read_b64_tr_b16 v[74:75], v225 offset:21504
	ds_read_b64_tr_b16 v[76:77], v225 offset:23040
	ds_read_b64_tr_b16 v[78:79], v225 offset:21568
	ds_read_b64_tr_b16 v[80:81], v225 offset:23104
	s_nop 3
	v_max3_f32 v234, v50, v51, v52
	v_max3_f32 v234, v234, v53, v54
	v_max3_f32 v234, v234, v55, v56
	v_max3_f32 v234, v234, v57, v58
	v_max3_f32 v234, v234, v59, v60
	v_max3_f32 v234, v234, v61, v62
	v_max3_f32 v234, v234, v63, v64
	v_max3_f32 v235, v2, v3, v4
	v_max3_f32 v235, v235, v5, v6
	v_max3_f32 v235, v235, v7, v8
	v_max3_f32 v235, v235, v9, v10
	v_max3_f32 v235, v235, v11, v12
	v_max3_f32 v235, v235, v13, v14
	v_max3_f32 v235, v235, v15, v16
	v_max3_f32 v234, v234, v65, v17
	v_max_f32_e32 v234, v234, v235
	v_mov_b32_e32 v235, v234
	s_waitcnt lgkmcnt(7)
	ds_read_b64_tr_b16 v[82:83], v225 offset:24576
	ds_read_b64_tr_b16 v[84:85], v225 offset:26112
	ds_read_b64_tr_b16 v[86:87], v225 offset:24640
	ds_read_b64_tr_b16 v[88:89], v225 offset:26176
	ds_read_b64_tr_b16 v[90:91], v225 offset:27648
	ds_read_b64_tr_b16 v[92:93], v225 offset:29184
	ds_read_b64_tr_b16 v[94:95], v225 offset:27712
	ds_read_b64_tr_b16 v[96:97], v225 offset:29248
	v_permlane32_swap_b32_e32 v235, v234
	v_max_f32_e32 v234, v234, v235
	v_cmp_lt_f32_e32 vcc, 0, v234
	s_or_b64 vcc, s[14:15], vcc
	s_cbranch_vccz .Lm1_norescale
	v_cndmask_b32_e64 v235, 0, v242, s[14:15]
	v_max_f32_e32 v234, v235, v234
	v_sub_f32_e32 v235, v235, v234
	v_exp_f32_e32 v162, v235
	v_add_f32_e32 v194, v1, v234
	v_sub_f32_e32 v114, v50, v234
	v_exp_f32_e32 v114, v114
	v_sub_f32_e32 v98, v2, v234
	v_exp_f32_e32 v98, v98
	v_sub_f32_e32 v115, v51, v234
	v_exp_f32_e32 v115, v115
	v_sub_f32_e32 v99, v3, v234
	v_exp_f32_e32 v99, v99
	v_sub_f32_e32 v116, v52, v234
	v_exp_f32_e32 v116, v116
	v_sub_f32_e32 v100, v4, v234
	v_exp_f32_e32 v100, v100
	v_sub_f32_e32 v117, v53, v234
	v_exp_f32_e32 v117, v117
	v_sub_f32_e32 v101, v5, v234
	v_exp_f32_e32 v101, v101
	v_sub_f32_e32 v118, v54, v234
	v_exp_f32_e32 v118, v118
	v_sub_f32_e32 v102, v6, v234
	v_exp_f32_e32 v102, v102
	v_sub_f32_e32 v119, v55, v234
	v_exp_f32_e32 v119, v119
	v_sub_f32_e32 v103, v7, v234
	v_exp_f32_e32 v103, v103
	v_sub_f32_e32 v120, v56, v234
	v_exp_f32_e32 v120, v120
	v_sub_f32_e32 v104, v8, v234
	v_exp_f32_e32 v104, v104
	v_sub_f32_e32 v121, v57, v234
	v_exp_f32_e32 v121, v121
	v_sub_f32_e32 v105, v9, v234
	v_exp_f32_e32 v105, v105
	v_sub_f32_e32 v122, v58, v234
	v_exp_f32_e32 v122, v122
	v_sub_f32_e32 v106, v10, v234
	v_exp_f32_e32 v106, v106
	v_sub_f32_e32 v123, v59, v234
	v_exp_f32_e32 v123, v123
	v_sub_f32_e32 v107, v11, v234
	v_exp_f32_e32 v107, v107
	v_sub_f32_e32 v124, v60, v234
	v_exp_f32_e32 v124, v124
	v_sub_f32_e32 v108, v12, v234
	v_exp_f32_e32 v108, v108
	v_sub_f32_e32 v125, v61, v234
	v_exp_f32_e32 v125, v125
	v_sub_f32_e32 v109, v13, v234
	v_exp_f32_e32 v109, v109
	v_sub_f32_e32 v126, v62, v234
	v_exp_f32_e32 v126, v126
	v_sub_f32_e32 v110, v14, v234
	v_exp_f32_e32 v110, v110
	v_sub_f32_e32 v127, v63, v234
	v_exp_f32_e32 v127, v127
	v_sub_f32_e32 v111, v15, v234
	v_exp_f32_e32 v111, v111
	v_sub_f32_e32 v128, v64, v234
	v_exp_f32_e32 v128, v128
	v_sub_f32_e32 v112, v16, v234
	v_exp_f32_e32 v112, v112
	v_sub_f32_e32 v129, v65, v234
	v_exp_f32_e32 v129, v129
	v_sub_f32_e32 v113, v17, v234
	v_exp_f32_e32 v113, v113
	v_pk_mul_f32 v[18:19], v[18:19], v[162:163] op_sel_hi:[1,0]
	v_pk_mul_f32 v[20:21], v[20:21], v[162:163] op_sel_hi:[1,0]
	v_pk_mul_f32 v[22:23], v[22:23], v[162:163] op_sel_hi:[1,0]
	v_pk_mul_f32 v[24:25], v[24:25], v[162:163] op_sel_hi:[1,0]
	v_pk_mul_f32 v[26:27], v[26:27], v[162:163] op_sel_hi:[1,0]
	v_pk_mul_f32 v[28:29], v[28:29], v[162:163] op_sel_hi:[1,0]
	v_pk_mul_f32 v[30:31], v[30:31], v[162:163] op_sel_hi:[1,0]
	v_pk_mul_f32 v[32:33], v[32:33], v[162:163] op_sel_hi:[1,0]
	v_pk_mul_f32 v[34:35], v[34:35], v[162:163] op_sel_hi:[1,0]
	v_pk_mul_f32 v[36:37], v[36:37], v[162:163] op_sel_hi:[1,0]
	v_pk_mul_f32 v[38:39], v[38:39], v[162:163] op_sel_hi:[1,0]
	v_pk_mul_f32 v[40:41], v[40:41], v[162:163] op_sel_hi:[1,0]
	v_pk_mul_f32 v[42:43], v[42:43], v[162:163] op_sel_hi:[1,0]
	v_pk_mul_f32 v[44:45], v[44:45], v[162:163] op_sel_hi:[1,0]
	v_pk_mul_f32 v[46:47], v[46:47], v[162:163] op_sel_hi:[1,0]
	v_pk_mul_f32 v[48:49], v[48:49], v[162:163] op_sel_hi:[1,0]
	s_branch .Lm1_pv

; #define LAS __attribute__((address_space(3)))
; template <int MODE  > ...
;     ...
;                 { typedef float f32x8 __attribute__((ext_vector_type(8)));
;                   const f32x16 t16 = s0 + s1;
;                   const f32x8 t8 = __builtin_shufflevector(t16, t16, 0, 1, 2, 3, 4, 5, 6, 7) + __builtin_shufflevector(t16, t16, 8, 9, 10, 11, 12, 13, 14, 15);
;                   const f32x4 t4 = __builtin_shufflevector(t8, t8, 0, 1, 2, 3) + __builtin_shufflevector(t8, t8, 4, 5, 6, 7);
;                   float ps = (t4[0] + t4[1]) + (t4[2] + t4[3]);
;                   ps += shflx(ps, 32, lane);
;                   st.l = st.l * alpha + ps; }
;                 bf16x8 pf[4];
; #pragma unroll
;                 for (int kk = 0; kk < 4; ++kk) {
;                     u32x4 pw;
;                     if (kk < 2) { pw.x = pk2(s0[8 * kk], s0[8 * kk + 1]); pw.y = pk2(s0[8 * kk + 2], s0[8 * kk + 3]); pw.z = pk2(s0[8 * kk + 4], s0[8 * kk + 5]); pw.w = pk2(s0[8 * kk + 6], s0[8 * kk + 7]); }
;                     else { const int k2 = kk - 2; pw.x = pk2(s1[8 * k2], s1[8 * k2 + 1]); pw.y = pk2(s1[8 * k2 + 2], s1[8 * k2 + 3]); pw.z = pk2(s1[8 * k2 + 4], s1[8 * k2 + 5]); pw.w = pk2(s1[8 * k2 + 6], s1[8 * k2 + 7]); }
;                     pf[kk] = __builtin_bit_cast(bf16x8, pw);
;                 }
;                 const LAS bf16_t* vb = (const LAS bf16_t*)(lds + A_VBUF) + cur * 64 * VPITCH + (4 * h + ((lane & 15) >> 2)) * VPITCH + ((lane >> 4) & 1) * 16 + 4 * (lane & 3);
; #pragma unroll
;                 for (int kk = 0; kk < 4; ++kk) {
;                     typedef short v4i16_t __attribute__((ext_vector_type(4)));
;                     const v4i16_t a0 = __builtin_amdgcn_ds_read_tr16_b64_v4i16((LAS v4i16_t*)(vb + (16 * kk) * VPITCH));
;                     const v4i16_t a1 = __builtin_amdgcn_ds_read_tr16_b64_v4i16((LAS v4i16_t*)(vb + (16 * kk + 8) * VPITCH));
;                     const v4i16_t b0 = __builtin_amdgcn_ds_read_tr16_b64_v4i16((LAS v4i16_t*)(vb + (16 * kk) * VPITCH + 32));
;                     const v4i16_t b1 = __builtin_amdgcn_ds_read_tr16_b64_v4i16((LAS v4i16_t*)(vb + (16 * kk + 8) * VPITCH + 32));
;                     const bf16x8 va = __builtin_shufflevector(a0, a1, 0, 1, 2, 3, 4, 5, 6, 7), vb8 = __builtin_shufflevector(b0, b1, 0, 1, 2, 3, 4, 5, 6, 7);
;                     st.o0 = __builtin_amdgcn_mfma_f32_32x32x16_bf16(va, pf[kk], st.o0, 0, 0, 0);
.Lm1_pv:
	v_cvt_pk_bf16_f32 v50, v114, v115
	v_cvt_pk_bf16_f32 v51, v116, v117
	v_cvt_pk_bf16_f32 v52, v118, v119
	v_cvt_pk_bf16_f32 v53, v120, v121
	s_waitcnt lgkmcnt(0)
	s_nop 0
	v_mfma_f32_32x32x16_bf16 v[18:33], v[66:69], v[50:53], v[18:33]
	v_mfma_f32_32x32x16_bf16 v[34:49], v[70:73], v[50:53], v[34:49]
	v_cvt_pk_bf16_f32 v54, v122, v123
	v_cvt_pk_bf16_f32 v55, v124, v125
	v_cvt_pk_bf16_f32 v56, v126, v127
	v_cvt_pk_bf16_f32 v57, v128, v129
	v_pk_add_f32 v[16:17], v[98:99], v[114:115]
	v_pk_add_f32 v[14:15], v[102:103], v[118:119]
	v_pk_add_f32 v[2:3], v[106:107], v[122:123]
	v_pk_add_f32 v[12:13], v[110:111], v[126:127]
	v_pk_add_f32 v[10:11], v[104:105], v[120:121]
	v_mfma_f32_32x32x16_bf16 v[18:33], v[74:77], v[54:57], v[18:33]
	v_mfma_f32_32x32x16_bf16 v[34:49], v[78:81], v[54:57], v[34:49]
	v_cvt_pk_bf16_f32 v58, v98, v99
	v_cvt_pk_bf16_f32 v59, v100, v101
	v_cvt_pk_bf16_f32 v60, v102, v103
	v_cvt_pk_bf16_f32 v61, v104, v105
	v_pk_add_f32 v[8:9], v[112:113], v[128:129]
	v_pk_add_f32 v[4:5], v[108:109], v[124:125]
	v_pk_add_f32 v[6:7], v[100:101], v[116:117]
	v_pk_add_f32 v[12:13], v[14:15], v[12:13]
	v_pk_add_f32 v[2:3], v[16:17], v[2:3]
	v_mfma_f32_32x32x16_bf16 v[18:33], v[82:85], v[58:61], v[18:33]
	v_mfma_f32_32x32x16_bf16 v[34:49], v[86:89], v[58:61], v[34:49]
	v_cvt_pk_bf16_f32 v62, v106, v107
	v_cvt_pk_bf16_f32 v63, v108, v109
	v_cvt_pk_bf16_f32 v64, v110, v111
	v_cvt_pk_bf16_f32 v65, v112, v113
	v_pk_add_f32 v[8:9], v[10:11], v[8:9]
	v_pk_add_f32 v[4:5], v[6:7], v[4:5]
	v_pk_add_f32 v[2:3], v[2:3], v[12:13]
	v_pk_add_f32 v[4:5], v[4:5], v[8:9]
	v_mfma_f32_32x32x16_bf16 v[18:33], v[90:93], v[62:65], v[18:33]
	v_mfma_f32_32x32x16_bf16 v[34:49], v[94:97], v[62:65], v[34:49]
	v_add_f32_e32 v2, v2, v3
	v_add_f32_e32 v3, v4, v5
	v_add_f32_e32 v2, v2, v3
	v_mov_b32_e32 v3, v2
	s_nop 1
	v_permlane32_swap_b32_e32 v3, v2
	v_add_f32_e32 v2, v2, v3
	v_fmac_f32_e32 v2, v193, v162
	v_mov_b32_e32 v193, v2

; template <int MODE  > ...
;     ...
;             for (int kk = 0; kk < 4; ++kk) {
;                 const bf16x8 k0 = *(const LAS bf16x8*)(kb + col * KPITCH + kk * 16 + h * 8);
;                 const bf16x8 k1 = *(const LAS bf16x8*)(kb + (32 + col) * KPITCH + kk * 16 + h * 8);
;                 s0 = __builtin_amdgcn_mfma_f32_32x32x16_bf16(k0, qf[kk], s0, 0, 0, 0);
;                 s1 = __builtin_amdgcn_mfma_f32_32x32x16_bf16(k1, qf[kk], s1, 0, 0, 0);
;             }
;             if (MODE != 3) {
;                 float mx = fmaxf(s0[0], s1[0]);
; #pragma unroll
;                 for (int i = 1; i < 16; ++i) mx = fmaxf(mx, fmaxf(s0[i], s1[i]));
;                 mx = fmaxf(mx, shflx(mx, 32, lane));
;                 float alpha = 1.f;
;                 if (__builtin_amdgcn_ballot_w64(fresh || mx > 0.f) != 0ull) {
;                     const float moldr = fresh ? -1e29f : 0.f, mnewr = fmaxf(moldr, mx);
;                     alpha = __builtin_amdgcn_exp2f(moldr - mnewr);
;                     st.m = mest + mnewr;
; #pragma unroll
;                     for (int i = 0; i < 16; ++i) { s0[i] = __builtin_amdgcn_exp2f(s0[i] - mnewr); s1[i] = __builtin_amdgcn_exp2f(s1[i] - mnewr); }
;                     st.o0 *= alpha; st.o1 *= alpha;
;                 } else {
; #pragma unroll
;                     for (int i = 0; i < 16; ++i) { s0[i] = __builtin_amdgcn_exp2f(s0[i]); s1[i] = __builtin_amdgcn_exp2f(s1[i]); }
;                 }
;                 { typedef float f32x8 __attribute__((ext_vector_type(8)));
;                   const f32x16 t16 = s0 + s1;
;                   const f32x8 t8 = __builtin_shufflevector(t16, t16, 0, 1, 2, 3, 4, 5, 6, 7) + __builtin_shufflevector(t16, t16, 8, 9, 10, 11, 12, 13, 14, 15);
;                   const f32x4 t4 = __builtin_shufflevector(t8, t8, 0, 1, 2, 3) + __builtin_shufflevector(t8, t8, 4, 5, 6, 7);
;                   float ps = (t4[0] + t4[1]) + (t4[2] + t4[3]);
;                   ps += shflx(ps, 32, lane);
;                   st.l = st.l * alpha + ps; }
;                 bf16x8 pf[4];
; #pragma unroll
;                 for (int kk = 0; kk < 4; ++kk) {
;                     u32x4 pw;
;                     if (kk < 2) { pw.x = pk2(s0[8 * kk], s0[8 * kk + 1]); pw.y = pk2(s0[8 * kk + 2], s0[8 * kk + 3]); pw.z = pk2(s0[8 * kk + 4], s0[8 * kk + 5]); pw.w = pk2(s0[8 * kk + 6], s0[8 * kk + 7]); }
.Lm2_qk:
	s_waitcnt lgkmcnt(7)
	v_mfma_f32_32x32x16_bf16 v[34:49], v[66:69], v[144:147], v[34:49]
	s_waitcnt lgkmcnt(6)
	v_mfma_f32_32x32x16_bf16 v[50:65], v[70:73], v[144:147], v[50:65]
	s_waitcnt lgkmcnt(5)
	v_mfma_f32_32x32x16_bf16 v[34:49], v[74:77], v[148:151], v[34:49]
	s_waitcnt lgkmcnt(4)
	v_mfma_f32_32x32x16_bf16 v[50:65], v[78:81], v[148:151], v[50:65]
	s_waitcnt lgkmcnt(3)
	v_mfma_f32_32x32x16_bf16 v[34:49], v[82:85], v[152:155], v[34:49]
	s_waitcnt lgkmcnt(2)
	v_mfma_f32_32x32x16_bf16 v[50:65], v[86:89], v[152:155], v[50:65]
	s_waitcnt lgkmcnt(1)
	v_mfma_f32_32x32x16_bf16 v[34:49], v[90:93], v[156:159], v[34:49]
	s_waitcnt lgkmcnt(0)
	v_mfma_f32_32x32x16_bf16 v[50:65], v[94:97], v[156:159], v[50:65]
	ds_read_b64_tr_b16 v[66:67], v225 offset:18432
	ds_read_b64_tr_b16 v[68:69], v225 offset:19968
	ds_read_b64_tr_b16 v[70:71], v225 offset:18496
	ds_read_b64_tr_b16 v[72:73], v225 offset:20032
	ds_read_b64_tr_b16 v[74:75], v225 offset:21504
	ds_read_b64_tr_b16 v[76:77], v225 offset:23040
	ds_read_b64_tr_b16 v[78:79], v225 offset:21568
	ds_read_b64_tr_b16 v[80:81], v225 offset:23104
	s_nop 3
	v_max3_f32 v234, v34, v35, v36
	v_max3_f32 v234, v234, v37, v38
	v_max3_f32 v234, v234, v39, v40
	v_max3_f32 v234, v234, v41, v42
	v_max3_f32 v234, v234, v43, v44
	v_max3_f32 v234, v234, v45, v46
	v_max3_f32 v234, v234, v47, v48
	v_max3_f32 v235, v50, v51, v52
	v_max3_f32 v235, v235, v53, v54
	v_max3_f32 v235, v235, v55, v56
	v_max3_f32 v235, v235, v57, v58
	v_max3_f32 v235, v235, v59, v60
	v_max3_f32 v235, v235, v61, v62
	v_max3_f32 v235, v235, v63, v64
	v_max3_f32 v234, v234, v49, v65
	v_max_f32_e32 v234, v234, v235
	v_mov_b32_e32 v235, v234
	s_waitcnt lgkmcnt(7)
	ds_read_b64_tr_b16 v[82:83], v225 offset:24576
	ds_read_b64_tr_b16 v[84:85], v225 offset:26112
	ds_read_b64_tr_b16 v[86:87], v225 offset:24640
	ds_read_b64_tr_b16 v[88:89], v225 offset:26176
	ds_read_b64_tr_b16 v[90:91], v225 offset:27648
	ds_read_b64_tr_b16 v[92:93], v225 offset:29184
	ds_read_b64_tr_b16 v[94:95], v225 offset:27712
	ds_read_b64_tr_b16 v[96:97], v225 offset:29248
	v_permlane32_swap_b32_e32 v235, v234
	v_max_f32_e32 v234, v234, v235
	v_cmp_lt_f32_e32 vcc, 0, v234
	s_or_b64 vcc, s[14:15], vcc
	s_cbranch_vccz .Lm2_norescale
	v_cndmask_b32_e64 v235, 0, v242, s[14:15]
	v_max_f32_e32 v234, v235, v234
	v_sub_f32_e32 v235, v235, v234
	v_exp_f32_e32 v160, v235
	v_add_f32_e32 v192, v1, v234
	v_sub_f32_e32 v114, v34, v234
	v_exp_f32_e32 v114, v114
	v_sub_f32_e32 v98, v50, v234
	v_exp_f32_e32 v98, v98
	v_sub_f32_e32 v115, v35, v234
	v_exp_f32_e32 v115, v115
	v_sub_f32_e32 v99, v51, v234
	v_exp_f32_e32 v99, v99
	v_sub_f32_e32 v116, v36, v234
	v_exp_f32_e32 v116, v116
	v_sub_f32_e32 v100, v52, v234
	v_exp_f32_e32 v100, v100
	v_sub_f32_e32 v117, v37, v234
	v_exp_f32_e32 v117, v117
	v_sub_f32_e32 v101, v53, v234
	v_exp_f32_e32 v101, v101
	v_sub_f32_e32 v118, v38, v234
	v_exp_f32_e32 v118, v118
	v_sub_f32_e32 v102, v54, v234
	v_exp_f32_e32 v102, v102
	v_sub_f32_e32 v119, v39, v234
	v_exp_f32_e32 v119, v119
	v_sub_f32_e32 v103, v55, v234
	v_exp_f32_e32 v103, v103
	v_sub_f32_e32 v120, v40, v234
	v_exp_f32_e32 v120, v120
	v_sub_f32_e32 v104, v56, v234
	v_exp_f32_e32 v104, v104
	v_sub_f32_e32 v121, v41, v234
	v_exp_f32_e32 v121, v121
	v_sub_f32_e32 v105, v57, v234
	v_exp_f32_e32 v105, v105
	v_sub_f32_e32 v122, v42, v234
	v_exp_f32_e32 v122, v122
	v_sub_f32_e32 v106, v58, v234
	v_exp_f32_e32 v106, v106
	v_sub_f32_e32 v123, v43, v234
	v_exp_f32_e32 v123, v123
	v_sub_f32_e32 v107, v59, v234
	v_exp_f32_e32 v107, v107
	v_sub_f32_e32 v124, v44, v234
	v_exp_f32_e32 v124, v124
	v_sub_f32_e32 v108, v60, v234
	v_exp_f32_e32 v108, v108
	v_sub_f32_e32 v125, v45, v234
	v_exp_f32_e32 v125, v125
	v_sub_f32_e32 v109, v61, v234
	v_exp_f32_e32 v109, v109
	v_sub_f32_e32 v126, v46, v234
	v_exp_f32_e32 v126, v126
	v_sub_f32_e32 v110, v62, v234
	v_exp_f32_e32 v110, v110
	v_sub_f32_e32 v127, v47, v234
	v_exp_f32_e32 v127, v127
	v_sub_f32_e32 v111, v63, v234
	v_exp_f32_e32 v111, v111
	v_sub_f32_e32 v128, v48, v234
	v_exp_f32_e32 v128, v128
	v_sub_f32_e32 v112, v64, v234
	v_exp_f32_e32 v112, v112
	v_sub_f32_e32 v129, v49, v234
	v_exp_f32_e32 v129, v129
	v_sub_f32_e32 v113, v65, v234
	v_exp_f32_e32 v113, v113
	v_pk_mul_f32 v[18:19], v[18:19], v[160:161] op_sel_hi:[1,0]
	v_pk_mul_f32 v[20:21], v[20:21], v[160:161] op_sel_hi:[1,0]
	v_pk_mul_f32 v[22:23], v[22:23], v[160:161] op_sel_hi:[1,0]
	v_pk_mul_f32 v[24:25], v[24:25], v[160:161] op_sel_hi:[1,0]
	v_pk_mul_f32 v[26:27], v[26:27], v[160:161] op_sel_hi:[1,0]
	v_pk_mul_f32 v[28:29], v[28:29], v[160:161] op_sel_hi:[1,0]
	v_pk_mul_f32 v[30:31], v[30:31], v[160:161] op_sel_hi:[1,0]
	v_pk_mul_f32 v[32:33], v[32:33], v[160:161] op_sel_hi:[1,0]
	v_pk_mul_f32 v[2:3], v[2:3], v[160:161] op_sel_hi:[1,0]
	v_pk_mul_f32 v[4:5], v[4:5], v[160:161] op_sel_hi:[1,0]
	v_pk_mul_f32 v[6:7], v[6:7], v[160:161] op_sel_hi:[1,0]
	v_pk_mul_f32 v[8:9], v[8:9], v[160:161] op_sel_hi:[1,0]
	v_pk_mul_f32 v[10:11], v[10:11], v[160:161] op_sel_hi:[1,0]
	v_pk_mul_f32 v[12:13], v[12:13], v[160:161] op_sel_hi:[1,0]
	v_pk_mul_f32 v[14:15], v[14:15], v[160:161] op_sel_hi:[1,0]
	v_pk_mul_f32 v[16:17], v[16:17], v[160:161] op_sel_hi:[1,0]
	s_branch .Lm2_pv

; #define LAS __attribute__((address_space(3)))
; template <int MODE  > ...
;     ...
;                 { typedef float f32x8 __attribute__((ext_vector_type(8)));
;                   const f32x16 t16 = s0 + s1;
;                   const f32x8 t8 = __builtin_shufflevector(t16, t16, 0, 1, 2, 3, 4, 5, 6, 7) + __builtin_shufflevector(t16, t16, 8, 9, 10, 11, 12, 13, 14, 15);
;                   const f32x4 t4 = __builtin_shufflevector(t8, t8, 0, 1, 2, 3) + __builtin_shufflevector(t8, t8, 4, 5, 6, 7);
;                   float ps = (t4[0] + t4[1]) + (t4[2] + t4[3]);
;                   ps += shflx(ps, 32, lane);
;                   st.l = st.l * alpha + ps; }
;                 bf16x8 pf[4];
; #pragma unroll
;                 for (int kk = 0; kk < 4; ++kk) {
;                     u32x4 pw;
;                     if (kk < 2) { pw.x = pk2(s0[8 * kk], s0[8 * kk + 1]); pw.y = pk2(s0[8 * kk + 2], s0[8 * kk + 3]); pw.z = pk2(s0[8 * kk + 4], s0[8 * kk + 5]); pw.w = pk2(s0[8 * kk + 6], s0[8 * kk + 7]); }
;                     else { const int k2 = kk - 2; pw.x = pk2(s1[8 * k2], s1[8 * k2 + 1]); pw.y = pk2(s1[8 * k2 + 2], s1[8 * k2 + 3]); pw.z = pk2(s1[8 * k2 + 4], s1[8 * k2 + 5]); pw.w = pk2(s1[8 * k2 + 6], s1[8 * k2 + 7]); }
;                     pf[kk] = __builtin_bit_cast(bf16x8, pw);
;                 }
;                 const LAS bf16_t* vb = (const LAS bf16_t*)(lds + A_VBUF) + cur * 64 * VPITCH + (4 * h + ((lane & 15) >> 2)) * VPITCH + ((lane >> 4) & 1) * 16 + 4 * (lane & 3);
; #pragma unroll
;                 for (int kk = 0; kk < 4; ++kk) {
;                     typedef short v4i16_t __attribute__((ext_vector_type(4)));
;                     const v4i16_t a0 = __builtin_amdgcn_ds_read_tr16_b64_v4i16((LAS v4i16_t*)(vb + (16 * kk) * VPITCH));
;                     const v4i16_t a1 = __builtin_amdgcn_ds_read_tr16_b64_v4i16((LAS v4i16_t*)(vb + (16 * kk + 8) * VPITCH));
;                     const v4i16_t b0 = __builtin_amdgcn_ds_read_tr16_b64_v4i16((LAS v4i16_t*)(vb + (16 * kk) * VPITCH + 32));
;                     const v4i16_t b1 = __builtin_amdgcn_ds_read_tr16_b64_v4i16((LAS v4i16_t*)(vb + (16 * kk + 8) * VPITCH + 32));
;                     const bf16x8 va = __builtin_shufflevector(a0, a1, 0, 1, 2, 3, 4, 5, 6, 7), vb8 = __builtin_shufflevector(b0, b1, 0, 1, 2, 3, 4, 5, 6, 7);
;                     st.o0 = __builtin_amdgcn_mfma_f32_32x32x16_bf16(va, pf[kk], st.o0, 0, 0, 0);
.Lm2_pv:
	v_cvt_pk_bf16_f32 v34, v114, v115
	v_cvt_pk_bf16_f32 v35, v116, v117
	v_cvt_pk_bf16_f32 v36, v118, v119
	v_cvt_pk_bf16_f32 v37, v120, v121
	s_waitcnt lgkmcnt(0)
	s_nop 0
	v_mfma_f32_32x32x16_bf16 v[18:33], v[66:69], v[34:37], v[18:33]
	v_mfma_f32_32x32x16_bf16 v[2:17], v[70:73], v[34:37], v[2:17]
	v_cvt_pk_bf16_f32 v38, v122, v123
	v_cvt_pk_bf16_f32 v39, v124, v125
	v_cvt_pk_bf16_f32 v40, v126, v127
	v_cvt_pk_bf16_f32 v41, v128, v129
	v_pk_add_f32 v[64:65], v[98:99], v[114:115]
	v_pk_add_f32 v[62:63], v[102:103], v[118:119]
	v_pk_add_f32 v[50:51], v[106:107], v[122:123]
	v_pk_add_f32 v[60:61], v[110:111], v[126:127]
	v_pk_add_f32 v[58:59], v[104:105], v[120:121]
	v_mfma_f32_32x32x16_bf16 v[18:33], v[74:77], v[38:41], v[18:33]
	v_mfma_f32_32x32x16_bf16 v[2:17], v[78:81], v[38:41], v[2:17]
	v_cvt_pk_bf16_f32 v42, v98, v99
	v_cvt_pk_bf16_f32 v43, v100, v101
	v_cvt_pk_bf16_f32 v44, v102, v103
	v_cvt_pk_bf16_f32 v45, v104, v105
	v_pk_add_f32 v[56:57], v[112:113], v[128:129]
	v_pk_add_f32 v[52:53], v[108:109], v[124:125]
	v_pk_add_f32 v[54:55], v[100:101], v[116:117]
	v_pk_add_f32 v[60:61], v[62:63], v[60:61]
	v_pk_add_f32 v[50:51], v[64:65], v[50:51]
	v_mfma_f32_32x32x16_bf16 v[18:33], v[82:85], v[42:45], v[18:33]
	v_mfma_f32_32x32x16_bf16 v[2:17], v[86:89], v[42:45], v[2:17]
	v_cvt_pk_bf16_f32 v46, v106, v107
	v_cvt_pk_bf16_f32 v47, v108, v109
	v_cvt_pk_bf16_f32 v48, v110, v111
	v_cvt_pk_bf16_f32 v49, v112, v113
	v_pk_add_f32 v[56:57], v[58:59], v[56:57]
	v_pk_add_f32 v[52:53], v[54:55], v[52:53]
	v_pk_add_f32 v[50:51], v[50:51], v[60:61]
	v_pk_add_f32 v[52:53], v[52:53], v[56:57]
	v_mfma_f32_32x32x16_bf16 v[18:33], v[90:93], v[46:49], v[18:33]
	v_mfma_f32_32x32x16_bf16 v[2:17], v[94:97], v[46:49], v[2:17]
	v_add_f32_e32 v50, v50, v51
	v_add_f32_e32 v51, v52, v53
	v_add_f32_e32 v50, v50, v51
	v_mov_b32_e32 v51, v50
	s_nop 1
	v_permlane32_swap_b32_e32 v51, v50
	v_add_f32_e32 v50, v50, v51
	v_fmac_f32_e32 v50, v190, v160
	v_mov_b32_e32 v190, v50
